# NSA partial sums kept in registers instead of an f32 scratch round trip through d_out; weight-transpose tiles (phases A and E): the 8 row loads unrolled so they are all in flight before one wait
# speedup vs baseline: 1.0679x; 1.0320x over previous
; DI void xpose_tile(int wv0, PP p, int jt, unsigned char* smem) {
;     ...
;   for (int kk = ty; kk < 64; kk += 8) {
;     float val = 0.f;
;     if (sc >= 0) val = src[(size_t)(k0 + kk) * Nsrc + sc];
;     if (scl) val *= scl[k0 + kk];
;     tile[kk * 65 + tx] = val;
;   }
.LBB0_120:
	s_mul_i32 s61, s61, s60
	s_sub_i32 s8, s23, s61
	v_ashrrev_i32_e32 v14, 6, v12
	s_lshl_b32 s16, s8, 6
	v_cmp_gt_i32_e32 vcc, 64, v14
	s_and_saveexec_b64 s[20:21], vcc
	s_cbranch_execz .LBB0_65
	v_cmp_lt_i32_e32 vcc, -1, v6
	s_waitcnt lgkmcnt(0)
	v_lshl_add_u64 v[10:11], v[6:7], 2, s[18:19]
	v_mul_lo_u32 v6, v14, s86
	v_lshlrev_b32_e32 v13, 2, v13
	v_add3_u32 v6, v6, v13, 32
	s_mov_b64 s[18:19], 0
	v_mov_b32_e32 v200, 0
	v_mov_b32_e32 v201, 0
	v_mov_b32_e32 v202, 0
	v_mov_b32_e32 v203, 0
	v_mov_b32_e32 v204, 0
	v_mov_b32_e32 v205, 0
	v_mov_b32_e32 v206, 0
	v_mov_b32_e32 v207, 0
	s_and_saveexec_b64 s[8:9], vcc
	s_cbranch_execz .Lmy_xpa_store
	v_add_u32_e32 v13, s16, v14
	v_ashrrev_i32_e32 v15, 31, v13
	v_mul_lo_u32 v15, s12, v15
	v_mul_lo_u32 v30, s13, v13
	v_mad_u64_u32 v[16:17], s[60:61], s12, v13, 0
	v_add3_u32 v17, v17, v15, v30
	v_lshl_add_u64 v[16:17], v[16:17], 2, v[10:11]
	global_load_dword v200, v[16:17], off
	v_add_u32_e32 v14, 8, v14
	v_add_u32_e32 v13, s16, v14
	v_ashrrev_i32_e32 v15, 31, v13
	v_mul_lo_u32 v15, s12, v15
	v_mul_lo_u32 v30, s13, v13
	v_mad_u64_u32 v[16:17], s[60:61], s12, v13, 0
	v_add3_u32 v17, v17, v15, v30
	v_lshl_add_u64 v[16:17], v[16:17], 2, v[10:11]
	global_load_dword v201, v[16:17], off
	v_add_u32_e32 v14, 8, v14
	v_add_u32_e32 v13, s16, v14
	v_ashrrev_i32_e32 v15, 31, v13
	v_mul_lo_u32 v15, s12, v15
	v_mul_lo_u32 v30, s13, v13
	v_mad_u64_u32 v[16:17], s[60:61], s12, v13, 0
	v_add3_u32 v17, v17, v15, v30
	v_lshl_add_u64 v[16:17], v[16:17], 2, v[10:11]
	global_load_dword v202, v[16:17], off
	v_add_u32_e32 v14, 8, v14
	v_add_u32_e32 v13, s16, v14
	v_ashrrev_i32_e32 v15, 31, v13
	v_mul_lo_u32 v15, s12, v15
	v_mul_lo_u32 v30, s13, v13
	v_mad_u64_u32 v[16:17], s[60:61], s12, v13, 0
	v_add3_u32 v17, v17, v15, v30
	v_lshl_add_u64 v[16:17], v[16:17], 2, v[10:11]
	global_load_dword v203, v[16:17], off
	v_add_u32_e32 v14, 8, v14
	v_add_u32_e32 v13, s16, v14
	v_ashrrev_i32_e32 v15, 31, v13
	v_mul_lo_u32 v15, s12, v15
	v_mul_lo_u32 v30, s13, v13
	v_mad_u64_u32 v[16:17], s[60:61], s12, v13, 0
	v_add3_u32 v17, v17, v15, v30
	v_lshl_add_u64 v[16:17], v[16:17], 2, v[10:11]
	global_load_dword v204, v[16:17], off
	v_add_u32_e32 v14, 8, v14
	v_add_u32_e32 v13, s16, v14
	v_ashrrev_i32_e32 v15, 31, v13
	v_mul_lo_u32 v15, s12, v15
	v_mul_lo_u32 v30, s13, v13
	v_mad_u64_u32 v[16:17], s[60:61], s12, v13, 0
	v_add3_u32 v17, v17, v15, v30
	v_lshl_add_u64 v[16:17], v[16:17], 2, v[10:11]
	global_load_dword v205, v[16:17], off
	v_add_u32_e32 v14, 8, v14
	v_add_u32_e32 v13, s16, v14
	v_ashrrev_i32_e32 v15, 31, v13
	v_mul_lo_u32 v15, s12, v15
	v_mul_lo_u32 v30, s13, v13
	v_mad_u64_u32 v[16:17], s[60:61], s12, v13, 0
	v_add3_u32 v17, v17, v15, v30
	v_lshl_add_u64 v[16:17], v[16:17], 2, v[10:11]
	global_load_dword v206, v[16:17], off
	v_add_u32_e32 v14, 8, v14
	v_add_u32_e32 v13, s16, v14
	v_ashrrev_i32_e32 v15, 31, v13
	v_mul_lo_u32 v15, s12, v15
	v_mul_lo_u32 v30, s13, v13
	v_mad_u64_u32 v[16:17], s[60:61], s12, v13, 0
	v_add3_u32 v17, v17, v15, v30
	v_lshl_add_u64 v[16:17], v[16:17], 2, v[10:11]
	global_load_dword v207, v[16:17], off
.Lmy_xpa_store:
	s_or_b64 exec, exec, s[8:9]
	s_waitcnt vmcnt(0)
	ds_write_b32 v6, v200
	ds_write_b32 v6, v201 offset:2080
	ds_write_b32 v6, v202 offset:4160
	ds_write_b32 v6, v203 offset:6240
	ds_write_b32 v6, v204 offset:8320
	ds_write_b32 v6, v205 offset:10400
	ds_write_b32 v6, v206 offset:12480
	ds_write_b32 v6, v207 offset:14560
	s_branch .LBB0_65

; DI void nsa_item(int wv0, PP p, int item, unsigned char* smem) {
;     ...
;   u16* NSAb = (u16*)(p->ws + OFF_NSA);
; #pragma unroll
;   for (int qt = 0; qt < 2; ++qt) {
;     float s = l[qt];
;     s += __shfl_xor(s, 16);
;     s += __shfl_xor(s, 32);
;     const float sc = NGb[ngoff + qt * 3 + 2] / s;
; #pragma unroll
;     for (int dt = 0; dt < 4; ++dt) {
;       const float4 a = *(const float4*)(ACCb + (aoff + qt * 64 + 16 * dt));
;       uint2 o;
;       o.x = pk2(a.x + O[qt][dt][0] * sc, a.y + O[qt][dt][1] * sc);
;       o.y = pk2(a.z + O[qt][dt][2] * sc, a.w + O[qt][dt][3] * sc);
;       *(uint2*)(NSAb + (aoff + qt * 64 + 16 * dt)) = o;
;     }
;   }
.LBB0_723:
	v_add_u32_e32 v2, 2, v142
	v_mov_b32_e32 v3, v1
	v_lshl_add_u64 v[2:3], v[2:3], 2, s[94:95]
	global_load_dword v0, v[2:3], off
	s_nop 0
	ds_bpermute_b32 v6, v144, v29
	v_readlane_b32 s45, v246, 15
	s_waitcnt lgkmcnt(0)
	v_add_f32_e32 v6, v29, v6
	ds_bpermute_b32 v7, v145, v6
	s_waitcnt lgkmcnt(0)
	v_add_f32_e32 v8, v6, v7
	v_lshl_add_u64 v[6:7], v[138:139], 1, s[78:79]
	s_waitcnt vmcnt(0)
	v_div_scale_f32 v9, s[2:3], v8, v8, v0
	v_rcp_f32_e32 v10, v9
	v_div_scale_f32 v11, vcc, v0, v8, v0
	v_fma_f32 v12, -v9, v10, 1.0
	v_fmac_f32_e32 v10, v12, v10
	v_mul_f32_e32 v12, v11, v10
	v_fma_f32 v13, -v9, v12, v11
	v_fmac_f32_e32 v12, v13, v10
	v_fma_f32 v9, -v9, v12, v11
	v_div_fmas_f32 v9, v9, v10, v12
	v_div_fixup_f32 v8, v9, v8, v0
	v_pk_fma_f32 v[2:3], v[104:105], v[8:9], v[218:219] op_sel_hi:[1,0,1]
	v_pk_fma_f32 v[4:5], v[106:107], v[8:9], v[220:221] op_sel_hi:[1,0,1]
	v_cvt_pk_bf16_f32 v2, v2, v3
	v_cvt_pk_bf16_f32 v3, v4, v5
	global_store_dwordx2 v[6:7], v[2:3], off
	v_or_b32_e32 v0, 16, v138
	v_lshl_add_u64 v[6:7], v[0:1], 1, s[78:79]
	v_add_u32_e32 v0, 5, v142
	v_lshl_add_u64 v[10:11], v[0:1], 2, s[94:95]
	v_pk_fma_f32 v[2:3], v[112:113], v[8:9], v[222:223] op_sel_hi:[1,0,1]
	v_pk_fma_f32 v[4:5], v[114:115], v[8:9], v[224:225] op_sel_hi:[1,0,1]
	v_cvt_pk_bf16_f32 v2, v2, v3
	v_cvt_pk_bf16_f32 v3, v4, v5
	global_store_dwordx2 v[6:7], v[2:3], off
	v_or_b32_e32 v6, 32, v138
	v_mov_b32_e32 v7, v1
	v_lshl_add_u64 v[6:7], v[6:7], 1, s[78:79]
	v_pk_fma_f32 v[2:3], v[120:121], v[8:9], v[226:227] op_sel_hi:[1,0,1]
	v_pk_fma_f32 v[4:5], v[122:123], v[8:9], v[228:229] op_sel_hi:[1,0,1]
	v_cvt_pk_bf16_f32 v2, v2, v3
	v_cvt_pk_bf16_f32 v3, v4, v5
	global_store_dwordx2 v[6:7], v[2:3], off
	v_or_b32_e32 v6, 48, v138
	v_mov_b32_e32 v7, v1
	v_lshl_add_u64 v[6:7], v[6:7], 1, s[78:79]
	v_pk_fma_f32 v[2:3], v[128:129], v[8:9], v[230:231] op_sel_hi:[1,0,1]
	v_pk_fma_f32 v[4:5], v[130:131], v[8:9], v[232:233] op_sel_hi:[1,0,1]
	v_cvt_pk_bf16_f32 v2, v2, v3
	v_cvt_pk_bf16_f32 v3, v4, v5
	global_store_dwordx2 v[6:7], v[2:3], off
	global_load_dword v0, v[10:11], off
	s_nop 0
	ds_bpermute_b32 v6, v144, v26
	v_mov_b32_e32 v7, v1
	s_waitcnt lgkmcnt(0)
	v_add_f32_e32 v8, v26, v6
	ds_bpermute_b32 v9, v145, v8
	v_or_b32_e32 v6, 64, v138
	v_lshl_add_u64 v[6:7], v[6:7], 1, s[78:79]
	s_waitcnt lgkmcnt(0)
	v_add_f32_e32 v8, v8, v9
	s_waitcnt vmcnt(0)
	v_div_scale_f32 v9, s[2:3], v8, v8, v0
	v_rcp_f32_e32 v10, v9
	v_div_scale_f32 v11, vcc, v0, v8, v0
	v_fma_f32 v12, -v9, v10, 1.0
	v_fmac_f32_e32 v10, v12, v10
	v_mul_f32_e32 v12, v11, v10
	v_fma_f32 v13, -v9, v12, v11
	v_fmac_f32_e32 v12, v13, v10
	v_fma_f32 v9, -v9, v12, v11
	v_div_fmas_f32 v9, v9, v10, v12
	v_div_fixup_f32 v0, v9, v8, v0
	v_pk_fma_f32 v[2:3], v[100:101], v[0:1], v[234:235] op_sel_hi:[1,0,1]
	v_pk_fma_f32 v[4:5], v[102:103], v[0:1], v[236:237] op_sel_hi:[1,0,1]
	v_cvt_pk_bf16_f32 v2, v2, v3
	v_cvt_pk_bf16_f32 v3, v4, v5
	global_store_dwordx2 v[6:7], v[2:3], off
	v_or_b32_e32 v6, 0x50, v138
	v_mov_b32_e32 v7, v1
	v_lshl_add_u64 v[6:7], v[6:7], 1, s[78:79]
	v_pk_fma_f32 v[2:3], v[108:109], v[0:1], v[238:239] op_sel_hi:[1,0,1]
	v_pk_fma_f32 v[4:5], v[110:111], v[0:1], v[240:241] op_sel_hi:[1,0,1]
	v_cvt_pk_bf16_f32 v2, v2, v3
	v_cvt_pk_bf16_f32 v3, v4, v5
	global_store_dwordx2 v[6:7], v[2:3], off
	v_or_b32_e32 v6, 0x60, v138
	v_mov_b32_e32 v7, v1
	v_lshl_add_u64 v[6:7], v[6:7], 1, s[78:79]
	v_pk_fma_f32 v[2:3], v[116:117], v[0:1], v[242:243] op_sel_hi:[1,0,1]
	v_pk_fma_f32 v[4:5], v[118:119], v[0:1], v[244:245] op_sel_hi:[1,0,1]
	v_cvt_pk_bf16_f32 v2, v2, v3
	v_cvt_pk_bf16_f32 v3, v4, v5
	global_store_dwordx2 v[6:7], v[2:3], off
	v_or_b32_e32 v6, 0x70, v138
	v_mov_b32_e32 v7, v1
	v_lshl_add_u64 v[6:7], v[6:7], 1, s[78:79]
	v_pk_fma_f32 v[2:3], v[124:125], v[0:1], v[248:249] op_sel_hi:[1,0,1]
	v_pk_fma_f32 v[4:5], v[126:127], v[0:1], v[250:251] op_sel_hi:[1,0,1]
	v_cvt_pk_bf16_f32 v2, v2, v3
	v_cvt_pk_bf16_f32 v3, v4, v5
	global_store_dwordx2 v[6:7], v[2:3], off
	s_barrier

; DI void xpose_tile(int wv0, PP p, int jt, unsigned char* smem) {
;     ...
;   for (int kk = ty; kk < 64; kk += 8) {
;     float val = 0.f;
;     if (sc >= 0) val = src[(size_t)(k0 + kk) * Nsrc + sc];
;     if (scl) val *= scl[k0 + kk];
;     tile[kk * 65 + tx] = val;
;   }
.LBB0_752:
	s_lshr_b32 s12, s17, 6
	s_ff1_i32_b32 s13, s12
	s_add_i32 s12, s12, -1
	s_lshr_b32 s13, s14, s13
	s_and_b32 s12, s14, s12
	s_and_b32 s13, s13, 0xffff
	s_lshl_b32 s12, s12, 6
	v_ashrrev_i32_e32 v0, 6, v6
	s_lshl_b32 s20, s13, 6
	s_and_b32 s19, s12, 0x3fffc0
	v_cmp_gt_i32_e32 vcc, 64, v0
	s_and_saveexec_b64 s[12:13], vcc
	s_cbranch_execz .LBB0_757
	v_and_b32_e32 v2, 63, v6
	v_or_b32_e32 v9, s20, v2
	s_waitcnt lgkmcnt(0)
	s_cmp_lg_u64 s[8:9], 0
	s_movk_i32 s21, 0x104
	v_add_u32_e32 v4, s19, v0
	s_load_dwordx2 s[22:23], s[10:11], 0x0
	s_cselect_b64 s[14:15], -1, 0
	v_add_u32_e32 v7, -8, v0
	v_mul_lo_u32 v3, v0, s21
	v_lshlrev_b32_e32 v2, 2, v2
	v_ashrrev_i32_e32 v5, 31, v4
	s_lshl_b32 s21, s6, 2
	v_lshlrev_b32_e32 v0, 2, v9
	v_add3_u32 v8, v3, v2, 32
	v_lshl_add_u64 v[2:3], v[4:5], 2, s[8:9]
	v_mad_u64_u32 v[10:11], s[8:9], s21, v4, v[0:1]
	s_lshr_b64 s[8:9], s[6:7], 30
	s_nop 0
	v_mul_lo_u32 v0, s8, v4
	v_mul_lo_u32 v4, s21, v5
	v_add3_u32 v11, v0, v11, v4
	s_mov_b64 s[10:11], 0
	s_waitcnt lgkmcnt(0)
	v_lshl_add_u64 v[4:5], s[22:23], 0, v[10:11]
	s_lshl_b64 s[6:7], s[6:7], 5
	global_load_dword v200, v[4:5], off
	v_lshl_add_u64 v[4:5], v[4:5], 0, s[6:7]
	global_load_dword v201, v[4:5], off
	v_lshl_add_u64 v[4:5], v[4:5], 0, s[6:7]
	global_load_dword v202, v[4:5], off
	v_lshl_add_u64 v[4:5], v[4:5], 0, s[6:7]
	global_load_dword v203, v[4:5], off
	v_lshl_add_u64 v[4:5], v[4:5], 0, s[6:7]
	global_load_dword v204, v[4:5], off
	v_lshl_add_u64 v[4:5], v[4:5], 0, s[6:7]
	global_load_dword v205, v[4:5], off
	v_lshl_add_u64 v[4:5], v[4:5], 0, s[6:7]
	global_load_dword v206, v[4:5], off
	v_lshl_add_u64 v[4:5], v[4:5], 0, s[6:7]
	global_load_dword v207, v[4:5], off
	s_andn2_b64 vcc, exec, s[14:15]
	s_cbranch_vccnz .Lmy_xpe_store
	global_load_dword v208, v[2:3], off
	v_lshl_add_u64 v[2:3], v[2:3], 0, 32
	global_load_dword v209, v[2:3], off
	v_lshl_add_u64 v[2:3], v[2:3], 0, 32
	global_load_dword v210, v[2:3], off
	v_lshl_add_u64 v[2:3], v[2:3], 0, 32
	global_load_dword v211, v[2:3], off
	v_lshl_add_u64 v[2:3], v[2:3], 0, 32
	global_load_dword v212, v[2:3], off
	v_lshl_add_u64 v[2:3], v[2:3], 0, 32
	global_load_dword v213, v[2:3], off
	v_lshl_add_u64 v[2:3], v[2:3], 0, 32
	global_load_dword v214, v[2:3], off
	v_lshl_add_u64 v[2:3], v[2:3], 0, 32
	global_load_dword v215, v[2:3], off
	s_waitcnt vmcnt(0)
	v_mul_f32_e32 v200, v200, v208
	v_mul_f32_e32 v201, v201, v209
	v_mul_f32_e32 v202, v202, v210
	v_mul_f32_e32 v203, v203, v211
	v_mul_f32_e32 v204, v204, v212
	v_mul_f32_e32 v205, v205, v213
	v_mul_f32_e32 v206, v206, v214
	v_mul_f32_e32 v207, v207, v215
.Lmy_xpe_store:
	s_waitcnt vmcnt(0)
	ds_write_b32 v8, v200
	ds_write_b32 v8, v201 offset:2080
	ds_write_b32 v8, v202 offset:4160
	ds_write_b32 v8, v203 offset:6240
	ds_write_b32 v8, v204 offset:8320
	ds_write_b32 v8, v205 offset:10400
	ds_write_b32 v8, v206 offset:12480
	ds_write_b32 v8, v207 offset:14560

; DI void nsa_item(int wv0, PP p, int item, unsigned char* smem) {
;     ...
; #pragma unroll
;     for (int qt = 0; qt < 2; ++qt) {
;       const float gt = NGb[ngoff + qt * 3 + 0];
; #pragma unroll
;       for (int dt = 0; dt < 4; ++dt) {
;         float4 o = make_float4(O[qt][dt][0] * gt, O[qt][dt][1] * gt, O[qt][dt][2] * gt, O[qt][dt][3] * gt);
;         *(float4*)(ACCb + (aoff + qt * 64 + 16 * dt)) = o;
;       }
;     }
;   }
;   __syncthreads();
;   u64 mlo = 0, mhi = 0, wlo = 0, whi = 0;
;   if (i < 16) {
;     mlo = (1ull << (i + 1)) - 1ull;
;     wlo = mlo;
;   } else {
;     const bool v0 = lane <= i, v1 = (lane + 64) <= i;
;     const bool f0 = (lane == 0) || (lane == i) || (lane == i - 1);
;     const bool f1 = (lane + 64 == i) || (lane + 64 == i - 1);
;     const u64 ltm = (1ull << lane) - 1ull;
.LBB0_813:
	s_mul_i32 s2, s40, 12
	v_readlane_b32 s3, v247, 49
	s_add_i32 s2, s2, s3
	v_mov_b32_e32 v2, s2
	v_mad_u64_u32 v[142:143], s[2:3], v74, 24, v[2:3]
	v_mov_b32_e32 v143, v1
	v_lshl_add_u64 v[2:3], v[142:143], 2, s[94:95]
	global_load_dword v16, v[2:3], off
	v_readlane_b32 s2, v247, 5
	v_readlane_b32 s3, v247, 6
	s_load_dwordx2 s[2:3], s[2:3], 0xc0
	v_or_b32_e32 v138, v72, v153
	v_mov_b32_e32 v139, v1
	v_mov_b32_e32 v3, v1
	v_add_u32_e32 v2, 3, v142
	s_waitcnt lgkmcnt(0)
	v_lshl_add_u64 v[140:141], v[138:139], 2, s[2:3]
	s_waitcnt vmcnt(1)
	v_lshl_add_u64 v[34:35], v[2:3], 2, s[94:95]
	s_mov_b64 s[2:3], -1
	s_cmpk_lt_i32 s88, 0x70
	v_cmp_eq_u32_e32 vcc, 0, v71
	s_waitcnt vmcnt(0)
	v_pk_mul_f32 v[2:3], v[54:55], v[16:17] op_sel_hi:[1,0]
	v_pk_mul_f32 v[4:5], v[56:57], v[16:17] op_sel_hi:[1,0]
	v_pk_mul_f32 v[6:7], v[50:51], v[16:17] op_sel_hi:[1,0]
	v_pk_mul_f32 v[8:9], v[52:53], v[16:17] op_sel_hi:[1,0]
	v_pk_mul_f32 v[10:11], v[46:47], v[16:17] op_sel_hi:[1,0]
	v_pk_mul_f32 v[12:13], v[48:49], v[16:17] op_sel_hi:[1,0]
	v_pk_mul_f32 v[14:15], v[42:43], v[16:17] op_sel_hi:[1,0]
	v_pk_mul_f32 v[16:17], v[44:45], v[16:17] op_sel_hi:[1,0]
	v_mov_b64_e32 v[218:219], v[2:3]
	v_mov_b64_e32 v[220:221], v[4:5]
	v_mov_b64_e32 v[222:223], v[6:7]
	v_mov_b64_e32 v[224:225], v[8:9]
	v_mov_b64_e32 v[226:227], v[10:11]
	v_mov_b64_e32 v[228:229], v[12:13]
	v_mov_b64_e32 v[230:231], v[14:15]
	v_mov_b64_e32 v[232:233], v[16:17]
	global_load_dword v16, v[34:35], off
	s_waitcnt vmcnt(0)
	v_pk_mul_f32 v[2:3], v[30:31], v[16:17] op_sel_hi:[1,0]
	v_pk_mul_f32 v[4:5], v[32:33], v[16:17] op_sel_hi:[1,0]
	v_pk_mul_f32 v[6:7], v[26:27], v[16:17] op_sel_hi:[1,0]
	v_pk_mul_f32 v[8:9], v[28:29], v[16:17] op_sel_hi:[1,0]
	v_pk_mul_f32 v[10:11], v[22:23], v[16:17] op_sel_hi:[1,0]
	v_pk_mul_f32 v[12:13], v[24:25], v[16:17] op_sel_hi:[1,0]
	v_pk_mul_f32 v[14:15], v[18:19], v[16:17] op_sel_hi:[1,0]
	v_pk_mul_f32 v[16:17], v[20:21], v[16:17] op_sel_hi:[1,0]
	v_mov_b64_e32 v[234:235], v[2:3]
	v_mov_b64_e32 v[236:237], v[4:5]
	v_mov_b64_e32 v[238:239], v[6:7]
	v_mov_b64_e32 v[240:241], v[8:9]
	v_mov_b64_e32 v[242:243], v[10:11]
	v_mov_b64_e32 v[244:245], v[12:13]
	v_mov_b64_e32 v[248:249], v[14:15]
	v_mov_b64_e32 v[250:251], v[16:17]
	s_barrier
	s_cbranch_scc0 .LBB0_820
	v_cmp_eq_u32_e64 s[10:11], s33, v71
	s_sub_i32 s14, 0x7e, s88
	s_or_b64 s[12:13], vcc, s[10:11]
	v_cmp_eq_u32_e64 s[10:11], s14, v71
	v_or_b32_e32 v2, 64, v71
	s_or_b64 s[10:11], s[12:13], s[10:11]
	v_cndmask_b32_e64 v4, 0, v149, s[10:11]
	v_cmp_eq_u32_e64 s[10:11], s33, v2
	v_cmp_eq_u32_e64 s[12:13], s14, v2
	s_or_b64 s[10:11], s[10:11], s[12:13]
	v_cmp_lt_i32_e64 s[6:7], s33, v2
	v_cmp_ge_i32_e64 s[8:9], s33, v2
	v_cndmask_b32_e64 v5, 0, v149, s[10:11]
	v_lshlrev_b64 v[2:3], v71, -1
	v_readlane_b32 s10, v246, 7
	v_cmp_lt_i32_e64 s[2:3], s33, v71
	v_cmp_ge_i32_e64 s[4:5], s33, v71
	v_not_b32_e32 v3, v3
	v_not_b32_e32 v2, v2
	v_lshl_add_u32 v6, v71, 2, s10
	s_mov_b64 s[20:21], 0
	s_mov_b32 s24, 8
	v_readlane_b32 s25, v246, 6
	s_mov_b64 s[22:23], 0
	s_branch .LBB0_816

; #define MAKE_RSRC(PTR) __builtin_amdgcn_make_buffer_rsrc((void*)(PTR), 0, 0x7fffffff, 0x00020000)
; #define ISSUE_TILE(RK, RV, T, LDV)                                                   \
;   {                                                                                  \
;     pk0 = BLOAD(RK, koff, (T)*8192);                                                 \
;     pv0 = BLOAD(RV, ((LDV) == 512) ? voffc : voffs, (T)*128);                        \
;   }
; DI void nsa_item(int wv0, PP p, int item, unsigned char* smem) {
;     ...
; #pragma unroll
;   for (int qt = 0; qt < 2; ++qt) {
;     float s = l[qt];
;     s += __shfl_xor(s, 16);
;     s += __shfl_xor(s, 32);
;     const float sc = NGb[ngoff + qt * 3 + 1] / s;
; #pragma unroll
;     for (int dt = 0; dt < 4; ++dt) {
;       float4* a = (float4*)(ACCb + (aoff + qt * 64 + 16 * dt));
;       float4 o = *a;
;       o.x += O[qt][dt][0] * sc; o.y += O[qt][dt][1] * sc; o.z += O[qt][dt][2] * sc; o.w += O[qt][dt][3] * sc;
;       *a = o;
;     }
;   }
;   RESET_STATE()
;   if (usefix) { m[0] = nb_w[0]; m[1] = nb_w[1]; }
;   {
;     const __amdgpu_buffer_rsrc_t rK = MAKE_RSRC((const u16*)(p->ws + OFF_KW) + (size_t)bg * S_ * 64);
;     const __amdgpu_buffer_rsrc_t rV = MAKE_RSRC((const u16*)(p->ws + OFF_VWT) + (size_t)bg * 64 * S_);
;     const int j0 = i >= 8 ? i - 8 : 0;
;     ISSUE_TILE(rK, rV, j0, S_)
;     COMMIT_BUF(0)
;     __syncthreads();
;     if (j0 + 1 <= i) ISSUE_TILE(rK, rV, j0 + 1, S_)
.LBB0_900:
	ds_bpermute_b32 v2, v144, v163
	v_or_b32_e32 v0, 1, v142
	s_lshl_b32 s2, s84, 19
	s_lshl_b32 s2, s2, 1
	v_readlane_b32 s3, v247, 63
	s_waitcnt lgkmcnt(0)
	v_add_f32_e32 v2, v163, v2
	ds_bpermute_b32 v3, v145, v2
	s_add_u32 s68, s3, s2
	v_readlane_b32 s3, v246, 0
	s_addc_u32 s3, s3, 0
	s_and_b32 s69, s3, 0xffff
	s_waitcnt lgkmcnt(0)
	v_add_f32_e32 v20, v2, v3
	v_lshl_add_u64 v[2:3], v[0:1], 2, s[94:95]
	global_load_dword v0, v[2:3], off
	v_readlane_b32 s3, v246, 1
	s_add_u32 s72, s3, s2
	v_readlane_b32 s2, v246, 2
	s_addc_u32 s2, s2, 0
	s_and_b32 s73, s2, 0xffff
	s_sub_i32 s2, 0x77, s88
	s_cmpk_lt_i32 s88, 0x78
	s_cselect_b32 s2, s2, 0
	s_mov_b32 s74, s70
	s_mov_b32 s75, s71
	s_lshl_b32 s3, s2, 13
	s_waitcnt vmcnt(0)
	v_div_scale_f32 v2, s[4:5], v20, v20, v0
	v_rcp_f32_e32 v3, v2
	s_nop 0
	v_fma_f32 v21, -v2, v3, 1.0
	v_fmac_f32_e32 v3, v21, v3
	v_div_scale_f32 v21, vcc, v0, v20, v0
	v_mul_f32_e32 v22, v21, v3
	v_fma_f32 v23, -v2, v22, v21
	v_fmac_f32_e32 v22, v23, v3
	v_fma_f32 v2, -v2, v22, v21
	v_div_fmas_f32 v2, v2, v3, v22
	v_div_fixup_f32 v0, v2, v20, v0
	v_pk_fma_f32 v[218:219], v[58:59], v[0:1], v[218:219] op_sel_hi:[1,0,1]
	v_pk_fma_f32 v[220:221], v[60:61], v[0:1], v[220:221] op_sel_hi:[1,0,1]
	v_pk_fma_f32 v[222:223], v[54:55], v[0:1], v[222:223] op_sel_hi:[1,0,1]
	v_pk_fma_f32 v[224:225], v[56:57], v[0:1], v[224:225] op_sel_hi:[1,0,1]
	v_pk_fma_f32 v[226:227], v[50:51], v[0:1], v[226:227] op_sel_hi:[1,0,1]
	v_pk_fma_f32 v[228:229], v[52:53], v[0:1], v[228:229] op_sel_hi:[1,0,1]
	v_pk_fma_f32 v[230:231], v[46:47], v[0:1], v[230:231] op_sel_hi:[1,0,1]
	v_pk_fma_f32 v[232:233], v[48:49], v[0:1], v[232:233] op_sel_hi:[1,0,1]
	ds_bpermute_b32 v0, v144, v162
	s_waitcnt lgkmcnt(0)
	v_add_f32_e32 v0, v162, v0
	ds_bpermute_b32 v2, v145, v0
	s_waitcnt lgkmcnt(0)
	v_add_f32_e32 v20, v0, v2
	v_add_u32_e32 v0, 4, v142
	v_lshl_add_u64 v[2:3], v[0:1], 2, s[94:95]
	global_load_dword v0, v[2:3], off
	s_waitcnt vmcnt(0)
	v_div_scale_f32 v2, s[4:5], v20, v20, v0
	v_rcp_f32_e32 v3, v2
	s_lshl_b32 s4, s2, 7
	s_cmp_ge_i32 s2, s33
	v_fma_f32 v21, -v2, v3, 1.0
	v_fmac_f32_e32 v3, v21, v3
	v_div_scale_f32 v21, vcc, v0, v20, v0
	v_mul_f32_e32 v22, v21, v3
	v_fma_f32 v23, -v2, v22, v21
	v_fmac_f32_e32 v22, v23, v3
	v_fma_f32 v2, -v2, v22, v21
	v_div_fmas_f32 v2, v2, v3, v22
	v_div_fixup_f32 v0, v2, v20, v0
	v_pk_fma_f32 v[234:235], v[42:43], v[0:1], v[234:235] op_sel_hi:[1,0,1]
	v_pk_fma_f32 v[236:237], v[44:45], v[0:1], v[236:237] op_sel_hi:[1,0,1]
	v_pk_fma_f32 v[238:239], v[38:39], v[0:1], v[238:239] op_sel_hi:[1,0,1]
	v_pk_fma_f32 v[240:241], v[40:41], v[0:1], v[240:241] op_sel_hi:[1,0,1]
	v_pk_fma_f32 v[242:243], v[34:35], v[0:1], v[242:243] op_sel_hi:[1,0,1]
	v_pk_fma_f32 v[244:245], v[36:37], v[0:1], v[244:245] op_sel_hi:[1,0,1]
	v_pk_fma_f32 v[248:249], v[30:31], v[0:1], v[248:249] op_sel_hi:[1,0,1]
	v_pk_fma_f32 v[250:251], v[32:33], v[0:1], v[250:251] op_sel_hi:[1,0,1]
	buffer_load_dwordx4 v[20:23], v152, s[68:71], s3 offen
	s_nop 0
	buffer_load_dwordx4 v[32:35], v143, s[72:75], s4 offen
	s_waitcnt vmcnt(1)
	ds_write_b128 v154, v[20:23]
	s_waitcnt vmcnt(0)
	ds_write_b128 v154, v[32:35] offset:9216
	s_waitcnt lgkmcnt(0)
	s_barrier
	s_cbranch_scc1 .LBB0_902
	s_add_i32 s5, s2, 1
	s_lshl_b32 s6, s5, 7
	s_lshl_b32 s5, s5, 13
	s_mov_b32 s74, s70
	s_mov_b32 s75, s71
	buffer_load_dwordx4 v[20:23], v152, s[68:71], s5 offen
	buffer_load_dwordx4 v[32:35], v143, s[72:75], s6 offen

; __global__ void __launch_bounds__(512, 2) mega(Params p) {
;   extern __shared__ __attribute__((aligned(16))) unsigned char smem[];
	.amdhsa_kernel _Z4mega6Params
		.amdhsa_group_segment_fixed_size 5152
		.amdhsa_private_segment_fixed_size 0
		.amdhsa_kernarg_size 472
		.amdhsa_user_sgpr_count 2
		.amdhsa_user_sgpr_dispatch_ptr 0
		.amdhsa_user_sgpr_queue_ptr 0
		.amdhsa_user_sgpr_kernarg_segment_ptr 1
		.amdhsa_user_sgpr_dispatch_id 0
		.amdhsa_user_sgpr_kernarg_preload_length 0
		.amdhsa_user_sgpr_kernarg_preload_offset 0
		.amdhsa_user_sgpr_private_segment_size 0
		.amdhsa_uses_dynamic_stack 0
		.amdhsa_enable_private_segment 0
		.amdhsa_system_sgpr_workgroup_id_x 1
		.amdhsa_system_sgpr_workgroup_id_y 0
		.amdhsa_system_sgpr_workgroup_id_z 0
		.amdhsa_system_sgpr_workgroup_info 0
		.amdhsa_system_vgpr_workitem_id 2
		.amdhsa_next_free_vgpr 256
		.amdhsa_next_free_sgpr 98
		.amdhsa_accum_offset 256
		.amdhsa_reserve_vcc 1
		.amdhsa_float_round_mode_32 0
		.amdhsa_float_round_mode_16_64 0
		.amdhsa_float_denorm_mode_32 3
		.amdhsa_float_denorm_mode_16_64 3
		.amdhsa_dx10_clamp 1
		.amdhsa_ieee_mode 1
		.amdhsa_fp16_overflow 0
		.amdhsa_tg_split 0
		.amdhsa_exception_fp_ieee_invalid_op 0
		.amdhsa_exception_fp_denorm_src 0
		.amdhsa_exception_fp_ieee_div_zero 0
		.amdhsa_exception_fp_ieee_overflow 0
		.amdhsa_exception_fp_ieee_underflow 0
		.amdhsa_exception_fp_ieee_inexact 0
		.amdhsa_exception_int_div_zero 0
	.end_amdhsa_kernel

; __global__ void __launch_bounds__(512, 2) mega(Params p) {
;   extern __shared__ __attribute__((aligned(16))) unsigned char smem[];
amdhsa.kernels:
  - .agpr_count:     0
    .args:
      - .offset:         0
        .size:           216
        .value_kind:     by_value
      - .offset:         216
        .size:           4
        .value_kind:     hidden_block_count_x
      - .offset:         220
        .size:           4
        .value_kind:     hidden_block_count_y
      - .offset:         224
        .size:           4
        .value_kind:     hidden_block_count_z
      - .offset:         228
        .size:           2
        .value_kind:     hidden_group_size_x
      - .offset:         230
        .size:           2
        .value_kind:     hidden_group_size_y
      - .offset:         232
        .size:           2
        .value_kind:     hidden_group_size_z
      - .offset:         234
        .size:           2
        .value_kind:     hidden_remainder_x
      - .offset:         236
        .size:           2
        .value_kind:     hidden_remainder_y
      - .offset:         238
        .size:           2
        .value_kind:     hidden_remainder_z
      - .offset:         256
        .size:           8
        .value_kind:     hidden_global_offset_x
      - .offset:         264
        .size:           8
        .value_kind:     hidden_global_offset_y
      - .offset:         272
        .size:           8
        .value_kind:     hidden_global_offset_z
      - .offset:         280
        .size:           2
        .value_kind:     hidden_grid_dims
      - .offset:         304
        .size:           8
        .value_kind:     hidden_multigrid_sync_arg
      - .offset:         336
        .size:           4
        .value_kind:     hidden_dynamic_lds_size
    .group_segment_fixed_size: 5152
    .kernarg_segment_align: 8
    .kernarg_segment_size: 472
    .language:       OpenCL C
    .language_version:
      - 2
      - 0
    .max_flat_workgroup_size: 512
    .name:           _Z4mega6Params
    .private_segment_fixed_size: 0
    .sgpr_count:     104
    .sgpr_spill_count: 86
    .symbol:         _Z4mega6Params.kd
    .uniform_work_group_size: 1
    .uses_dynamic_stack: false
    .vgpr_count:     256
    .vgpr_spill_count: 0
    .wavefront_size: 64
